# GEMM K-loop compute segments: no-op setprio pair between the two MFMA halves and the repeated lgkmcnt(0) after the barrier removed
# speedup vs baseline: 1.0042x; 1.0042x over previous
.LBB0_110:
	s_add_i32 s39, s10, 2
	s_add_u32 s40, s8, 0x80
	s_addc_u32 s11, s9, 0
	s_add_i32 s42, 0, 0x10000
	s_cmp_eq_u32 s82, s10
	s_cselect_b32 s11, s3, s11
	s_cselect_b32 s10, s2, s40
	v_add_u32_e32 v0, s42, v190
	s_cselect_b32 s41, s1, s38
	s_cselect_b32 s40, s0, s36
	s_add_i32 s43, 0, 0x14000
	ds_read_b128 v[130:133], v0
	ds_read_b128 v[134:137], v0 offset:1024
	ds_read_b128 v[138:141], v0 offset:2048
	ds_read_b128 v[142:145], v0 offset:3072
	v_add_u32_e32 v0, s43, v190
	ds_read_b128 v[146:149], v0
	ds_read_b128 v[162:165], v0 offset:1024
	ds_read_b128 v[166:169], v0 offset:2048
	ds_read_b128 v[192:195], v0 offset:3072
	v_lshl_add_u64 v[170:171], s[8:9], 0, v[158:159]
	s_add_i32 m0, s75, 0xc000
	ds_read_b128 v[196:199], v191
	ds_read_b128 v[200:203], v191 offset:1024
	ds_read_b128 v[204:207], v191 offset:2048
	ds_read_b128 v[208:211], v191 offset:3072
	ds_read_b128 v[212:215], v191 offset:4096
	ds_read_b128 v[216:219], v191 offset:5120
	ds_read_b128 v[220:223], v191 offset:6144
	ds_read_b128 v[224:227], v191 offset:7168
	global_load_lds_dwordx4 v[170:171], off
	v_lshl_add_u64 v[170:171], s[8:9], 0, v[160:161]
	s_add_i32 m0, s75, 0xe000
	s_nop 0
	global_load_lds_dwordx4 v[170:171], off
	s_waitcnt vmcnt(8)
	s_waitcnt lgkmcnt(0)
	s_barrier
	s_setprio 1
	v_mfma_f32_16x16x32_bf16 v[126:129], v[130:133], v[196:199], v[126:129]
	v_mfma_f32_16x16x32_bf16 v[122:125], v[138:141], v[196:199], v[122:125]
	v_mfma_f32_16x16x32_bf16 v[110:113], v[130:133], v[204:207], v[110:113]
	v_mfma_f32_16x16x32_bf16 v[106:109], v[138:141], v[204:207], v[106:109]
	v_mfma_f32_16x16x32_bf16 v[94:97], v[130:133], v[212:215], v[94:97]
	v_mfma_f32_16x16x32_bf16 v[90:93], v[138:141], v[212:215], v[90:93]
	v_mfma_f32_16x16x32_bf16 v[78:81], v[130:133], v[220:223], v[78:81]
	v_mfma_f32_16x16x32_bf16 v[74:77], v[138:141], v[220:223], v[74:77]
	v_mfma_f32_16x16x32_bf16 v[126:129], v[134:137], v[200:203], v[126:129]
	v_mfma_f32_16x16x32_bf16 v[122:125], v[142:145], v[200:203], v[122:125]
	v_mfma_f32_16x16x32_bf16 v[110:113], v[134:137], v[208:211], v[110:113]
	v_mfma_f32_16x16x32_bf16 v[106:109], v[142:145], v[208:211], v[106:109]
	v_mfma_f32_16x16x32_bf16 v[94:97], v[134:137], v[216:219], v[94:97]
	v_mfma_f32_16x16x32_bf16 v[90:93], v[142:145], v[216:219], v[90:93]
	v_mfma_f32_16x16x32_bf16 v[78:81], v[134:137], v[224:227], v[78:81]
	v_mfma_f32_16x16x32_bf16 v[74:77], v[142:145], v[224:227], v[74:77]
	v_mfma_f32_16x16x32_bf16 v[118:121], v[146:149], v[196:199], v[118:121]
	v_mfma_f32_16x16x32_bf16 v[114:117], v[166:169], v[196:199], v[114:117]
	v_mfma_f32_16x16x32_bf16 v[102:105], v[146:149], v[204:207], v[102:105]
	v_mfma_f32_16x16x32_bf16 v[98:101], v[166:169], v[204:207], v[98:101]
	v_mfma_f32_16x16x32_bf16 v[86:89], v[146:149], v[212:215], v[86:89]
	v_mfma_f32_16x16x32_bf16 v[82:85], v[166:169], v[212:215], v[82:85]
	v_mfma_f32_16x16x32_bf16 v[70:73], v[146:149], v[220:223], v[70:73]
	v_mfma_f32_16x16x32_bf16 v[66:69], v[166:169], v[220:223], v[66:69]
	v_mfma_f32_16x16x32_bf16 v[118:121], v[162:165], v[200:203], v[118:121]
	v_mfma_f32_16x16x32_bf16 v[114:117], v[192:195], v[200:203], v[114:117]
	v_mfma_f32_16x16x32_bf16 v[102:105], v[162:165], v[208:211], v[102:105]
	v_mfma_f32_16x16x32_bf16 v[98:101], v[192:195], v[208:211], v[98:101]
	v_mfma_f32_16x16x32_bf16 v[86:89], v[162:165], v[216:219], v[86:89]
	v_mfma_f32_16x16x32_bf16 v[82:85], v[192:195], v[216:219], v[82:85]
	v_mfma_f32_16x16x32_bf16 v[70:73], v[162:165], v[224:227], v[70:73]
	v_mfma_f32_16x16x32_bf16 v[66:69], v[192:195], v[224:227], v[66:69]
	s_setprio 0
	s_barrier
	s_add_i32 s42, s42, s74
	v_lshl_add_u64 v[170:171], s[40:41], 0, v[152:153]
	s_mov_b32 m0, s42
	ds_read_b128 v[196:199], v191 offset:16384
	ds_read_b128 v[200:203], v191 offset:17408
	ds_read_b128 v[204:207], v191 offset:18432
	ds_read_b128 v[208:211], v191 offset:19456
	ds_read_b128 v[212:215], v191 offset:20480
	ds_read_b128 v[216:219], v191 offset:21504
	ds_read_b128 v[220:223], v191 offset:22528
	ds_read_b128 v[224:227], v191 offset:23552
	global_load_lds_dwordx4 v[170:171], off
	s_add_i32 m0, s42, 0x2000
	v_lshl_add_u64 v[228:229], s[40:41], 0, v[156:157]
	s_add_u32 s40, s40, s20
	s_addc_u32 s41, s41, s21
	s_add_i32 s42, s43, s74
	global_load_lds_dwordx4 v[228:229], off
	v_lshl_add_u64 v[230:231], s[40:41], 0, v[152:153]
	s_mov_b32 m0, s42
	v_lshl_add_u64 v[232:233], s[40:41], 0, v[156:157]
	global_load_lds_dwordx4 v[230:231], off
	s_add_i32 m0, s42, 0x2000
	v_lshl_add_u64 v[234:235], s[10:11], 0, v[150:151]
	global_load_lds_dwordx4 v[232:233], off
	s_mov_b32 m0, s75
	v_lshl_add_u64 v[236:237], s[10:11], 0, v[154:155]
	global_load_lds_dwordx4 v[234:235], off
	s_mov_b32 m0, s71
	s_nop 0
	global_load_lds_dwordx4 v[236:237], off
	s_waitcnt vmcnt(8)
	s_waitcnt lgkmcnt(0)
	s_barrier
	s_setprio 1
	v_mfma_f32_16x16x32_bf16 v[62:65], v[130:133], v[196:199], v[62:65]
	v_mfma_f32_16x16x32_bf16 v[58:61], v[138:141], v[196:199], v[58:61]
	v_mfma_f32_16x16x32_bf16 v[46:49], v[130:133], v[204:207], v[46:49]
	v_mfma_f32_16x16x32_bf16 v[42:45], v[138:141], v[204:207], v[42:45]
	v_mfma_f32_16x16x32_bf16 v[30:33], v[130:133], v[212:215], v[30:33]
	v_mfma_f32_16x16x32_bf16 v[26:29], v[138:141], v[212:215], v[26:29]
	v_mfma_f32_16x16x32_bf16 v[14:17], v[130:133], v[220:223], v[14:17]
	v_mfma_f32_16x16x32_bf16 v[10:13], v[138:141], v[220:223], v[10:13]
	v_mfma_f32_16x16x32_bf16 v[62:65], v[134:137], v[200:203], v[62:65]
	v_mfma_f32_16x16x32_bf16 v[58:61], v[142:145], v[200:203], v[58:61]
	v_mfma_f32_16x16x32_bf16 v[46:49], v[134:137], v[208:211], v[46:49]
	v_mfma_f32_16x16x32_bf16 v[42:45], v[142:145], v[208:211], v[42:45]
	v_mfma_f32_16x16x32_bf16 v[30:33], v[134:137], v[216:219], v[30:33]
	v_mfma_f32_16x16x32_bf16 v[26:29], v[142:145], v[216:219], v[26:29]
	v_mfma_f32_16x16x32_bf16 v[14:17], v[134:137], v[224:227], v[14:17]
	v_mfma_f32_16x16x32_bf16 v[10:13], v[142:145], v[224:227], v[10:13]
	v_mfma_f32_16x16x32_bf16 v[54:57], v[146:149], v[196:199], v[54:57]
	v_mfma_f32_16x16x32_bf16 v[50:53], v[166:169], v[196:199], v[50:53]
	v_mfma_f32_16x16x32_bf16 v[38:41], v[146:149], v[204:207], v[38:41]
	v_mfma_f32_16x16x32_bf16 v[34:37], v[166:169], v[204:207], v[34:37]
	v_mfma_f32_16x16x32_bf16 v[22:25], v[146:149], v[212:215], v[22:25]
	v_mfma_f32_16x16x32_bf16 v[18:21], v[166:169], v[212:215], v[18:21]
	v_mfma_f32_16x16x32_bf16 v[6:9], v[146:149], v[220:223], v[6:9]
	v_mfma_f32_16x16x32_bf16 v[2:5], v[166:169], v[220:223], v[2:5]
	v_mfma_f32_16x16x32_bf16 v[54:57], v[162:165], v[200:203], v[54:57]
	v_mfma_f32_16x16x32_bf16 v[50:53], v[192:195], v[200:203], v[50:53]
	v_mfma_f32_16x16x32_bf16 v[38:41], v[162:165], v[208:211], v[38:41]
	v_mfma_f32_16x16x32_bf16 v[34:37], v[192:195], v[208:211], v[34:37]
	v_mfma_f32_16x16x32_bf16 v[22:25], v[162:165], v[216:219], v[22:25]
	v_mfma_f32_16x16x32_bf16 v[18:21], v[192:195], v[216:219], v[18:21]
	v_mfma_f32_16x16x32_bf16 v[6:9], v[162:165], v[224:227], v[6:9]
	v_mfma_f32_16x16x32_bf16 v[2:5], v[192:195], v[224:227], v[2:5]
	s_setprio 0
	s_barrier
	s_add_i32 s40, 0, 0x18000
	v_add_u32_e32 v0, s40, v190
	s_add_i32 s41, 0, 0x1c000
	ds_read_b128 v[130:133], v0
	ds_read_b128 v[134:137], v0 offset:1024
	ds_read_b128 v[138:141], v0 offset:2048
	ds_read_b128 v[142:145], v0 offset:3072
	v_add_u32_e32 v0, s41, v190
	ds_read_b128 v[146:149], v0
	ds_read_b128 v[162:165], v0 offset:1024
	ds_read_b128 v[166:169], v0 offset:2048
	ds_read_b128 v[192:195], v0 offset:3072
	s_add_u32 s10, s10, s18
	s_addc_u32 s11, s11, s19
	s_mov_b32 m0, s89
	v_lshl_add_u64 v[238:239], s[10:11], 0, v[150:151]
	ds_read_b128 v[196:199], v191 offset:32768
	ds_read_b128 v[200:203], v191 offset:33792
	ds_read_b128 v[204:207], v191 offset:34816
	ds_read_b128 v[208:211], v191 offset:35840
	ds_read_b128 v[212:215], v191 offset:36864
	ds_read_b128 v[216:219], v191 offset:37888
	ds_read_b128 v[220:223], v191 offset:38912
	ds_read_b128 v[224:227], v191 offset:39936
	global_load_lds_dwordx4 v[238:239], off
	v_lshl_add_u64 v[238:239], s[10:11], 0, v[154:155]
	s_mov_b32 m0, s79
	s_nop 0
	global_load_lds_dwordx4 v[238:239], off
	s_waitcnt vmcnt(8)
	s_waitcnt lgkmcnt(0)
	s_barrier
	s_setprio 1
	v_mfma_f32_16x16x32_bf16 v[126:129], v[130:133], v[196:199], v[126:129]
	v_mfma_f32_16x16x32_bf16 v[122:125], v[138:141], v[196:199], v[122:125]
	v_mfma_f32_16x16x32_bf16 v[110:113], v[130:133], v[204:207], v[110:113]
	v_mfma_f32_16x16x32_bf16 v[106:109], v[138:141], v[204:207], v[106:109]
	v_mfma_f32_16x16x32_bf16 v[94:97], v[130:133], v[212:215], v[94:97]
	v_mfma_f32_16x16x32_bf16 v[90:93], v[138:141], v[212:215], v[90:93]
	v_mfma_f32_16x16x32_bf16 v[78:81], v[130:133], v[220:223], v[78:81]
	v_mfma_f32_16x16x32_bf16 v[74:77], v[138:141], v[220:223], v[74:77]
	v_mfma_f32_16x16x32_bf16 v[126:129], v[134:137], v[200:203], v[126:129]
	v_mfma_f32_16x16x32_bf16 v[122:125], v[142:145], v[200:203], v[122:125]
	v_mfma_f32_16x16x32_bf16 v[110:113], v[134:137], v[208:211], v[110:113]
	v_mfma_f32_16x16x32_bf16 v[106:109], v[142:145], v[208:211], v[106:109]
	v_mfma_f32_16x16x32_bf16 v[94:97], v[134:137], v[216:219], v[94:97]
	v_mfma_f32_16x16x32_bf16 v[90:93], v[142:145], v[216:219], v[90:93]
	v_mfma_f32_16x16x32_bf16 v[78:81], v[134:137], v[224:227], v[78:81]
	v_mfma_f32_16x16x32_bf16 v[74:77], v[142:145], v[224:227], v[74:77]
	v_mfma_f32_16x16x32_bf16 v[118:121], v[146:149], v[196:199], v[118:121]
	v_mfma_f32_16x16x32_bf16 v[114:117], v[166:169], v[196:199], v[114:117]
	v_mfma_f32_16x16x32_bf16 v[102:105], v[146:149], v[204:207], v[102:105]
	v_mfma_f32_16x16x32_bf16 v[98:101], v[166:169], v[204:207], v[98:101]
	v_mfma_f32_16x16x32_bf16 v[86:89], v[146:149], v[212:215], v[86:89]
	v_mfma_f32_16x16x32_bf16 v[82:85], v[166:169], v[212:215], v[82:85]
	v_mfma_f32_16x16x32_bf16 v[70:73], v[146:149], v[220:223], v[70:73]
	v_mfma_f32_16x16x32_bf16 v[66:69], v[166:169], v[220:223], v[66:69]
	v_mfma_f32_16x16x32_bf16 v[118:121], v[162:165], v[200:203], v[118:121]
	v_mfma_f32_16x16x32_bf16 v[114:117], v[192:195], v[200:203], v[114:117]
	v_mfma_f32_16x16x32_bf16 v[102:105], v[162:165], v[208:211], v[102:105]
	v_mfma_f32_16x16x32_bf16 v[98:101], v[192:195], v[208:211], v[98:101]
	v_mfma_f32_16x16x32_bf16 v[86:89], v[162:165], v[216:219], v[86:89]
	v_mfma_f32_16x16x32_bf16 v[82:85], v[192:195], v[216:219], v[82:85]
	v_mfma_f32_16x16x32_bf16 v[70:73], v[162:165], v[224:227], v[70:73]
	v_mfma_f32_16x16x32_bf16 v[66:69], v[192:195], v[224:227], v[66:69]
	s_setprio 0
	s_barrier
	s_add_i32 s10, s40, s74
	v_lshl_add_u64 v[170:171], v[170:171], 0, s[56:57]
	s_mov_b32 m0, s10
	ds_read_b128 v[196:199], v191 offset:49152
	ds_read_b128 v[200:203], v191 offset:50176
	ds_read_b128 v[204:207], v191 offset:51200
	ds_read_b128 v[208:211], v191 offset:52224
	ds_read_b128 v[212:215], v191 offset:53248
	ds_read_b128 v[216:219], v191 offset:54272
	ds_read_b128 v[220:223], v191 offset:55296
	ds_read_b128 v[224:227], v191 offset:56320
	global_load_lds_dwordx4 v[170:171], off
	v_lshl_add_u64 v[170:171], v[228:229], 0, s[56:57]
	s_add_i32 m0, s10, 0x2000
	s_add_i32 s10, s41, s74
	global_load_lds_dwordx4 v[170:171], off
	v_lshl_add_u64 v[170:171], v[230:231], 0, s[56:57]
	s_mov_b32 m0, s10
	s_nop 0
	global_load_lds_dwordx4 v[170:171], off
	v_lshl_add_u64 v[170:171], v[232:233], 0, s[56:57]
	s_add_i32 m0, s10, 0x2000
	s_nop 0
	global_load_lds_dwordx4 v[170:171], off
	v_lshl_add_u64 v[170:171], v[234:235], 0, s[56:57]
	s_mov_b32 m0, s26
	s_nop 0
	global_load_lds_dwordx4 v[170:171], off
	v_lshl_add_u64 v[170:171], v[236:237], 0, s[56:57]
	s_mov_b32 m0, s27
	s_nop 0
	global_load_lds_dwordx4 v[170:171], off
	s_waitcnt vmcnt(8)
	s_waitcnt lgkmcnt(0)
	s_barrier
	s_setprio 1
	v_mfma_f32_16x16x32_bf16 v[62:65], v[130:133], v[196:199], v[62:65]
	v_mfma_f32_16x16x32_bf16 v[58:61], v[138:141], v[196:199], v[58:61]
	v_mfma_f32_16x16x32_bf16 v[46:49], v[130:133], v[204:207], v[46:49]
	v_mfma_f32_16x16x32_bf16 v[42:45], v[138:141], v[204:207], v[42:45]
	v_mfma_f32_16x16x32_bf16 v[30:33], v[130:133], v[212:215], v[30:33]
	v_mfma_f32_16x16x32_bf16 v[26:29], v[138:141], v[212:215], v[26:29]
	v_mfma_f32_16x16x32_bf16 v[14:17], v[130:133], v[220:223], v[14:17]
	v_mfma_f32_16x16x32_bf16 v[10:13], v[138:141], v[220:223], v[10:13]
	v_mfma_f32_16x16x32_bf16 v[62:65], v[134:137], v[200:203], v[62:65]
	v_mfma_f32_16x16x32_bf16 v[58:61], v[142:145], v[200:203], v[58:61]
	v_mfma_f32_16x16x32_bf16 v[46:49], v[134:137], v[208:211], v[46:49]
	v_mfma_f32_16x16x32_bf16 v[42:45], v[142:145], v[208:211], v[42:45]
	v_mfma_f32_16x16x32_bf16 v[30:33], v[134:137], v[216:219], v[30:33]
	v_mfma_f32_16x16x32_bf16 v[26:29], v[142:145], v[216:219], v[26:29]
	v_mfma_f32_16x16x32_bf16 v[14:17], v[134:137], v[224:227], v[14:17]
	v_mfma_f32_16x16x32_bf16 v[10:13], v[142:145], v[224:227], v[10:13]
	v_mfma_f32_16x16x32_bf16 v[54:57], v[146:149], v[196:199], v[54:57]
	v_mfma_f32_16x16x32_bf16 v[50:53], v[166:169], v[196:199], v[50:53]
	v_mfma_f32_16x16x32_bf16 v[38:41], v[146:149], v[204:207], v[38:41]
	v_mfma_f32_16x16x32_bf16 v[34:37], v[166:169], v[204:207], v[34:37]
	v_mfma_f32_16x16x32_bf16 v[22:25], v[146:149], v[212:215], v[22:25]
	v_mfma_f32_16x16x32_bf16 v[18:21], v[166:169], v[212:215], v[18:21]
	v_mfma_f32_16x16x32_bf16 v[6:9], v[146:149], v[220:223], v[6:9]
	v_mfma_f32_16x16x32_bf16 v[2:5], v[166:169], v[220:223], v[2:5]
	v_mfma_f32_16x16x32_bf16 v[54:57], v[162:165], v[200:203], v[54:57]
	v_mfma_f32_16x16x32_bf16 v[50:53], v[192:195], v[200:203], v[50:53]
	v_mfma_f32_16x16x32_bf16 v[38:41], v[162:165], v[208:211], v[38:41]
	v_mfma_f32_16x16x32_bf16 v[34:37], v[192:195], v[208:211], v[34:37]
	v_mfma_f32_16x16x32_bf16 v[22:25], v[162:165], v[216:219], v[22:25]
	v_mfma_f32_16x16x32_bf16 v[18:21], v[192:195], v[216:219], v[18:21]
	v_mfma_f32_16x16x32_bf16 v[6:9], v[162:165], v[224:227], v[6:9]
	v_mfma_f32_16x16x32_bf16 v[2:5], v[192:195], v[224:227], v[2:5]
	s_setprio 0
	s_barrier
	s_add_u32 s8, s8, 0x100
	s_addc_u32 s9, s9, 0
	s_add_u32 s36, s36, 0x100
	s_addc_u32 s38, s38, 0
	s_cmp_ge_u32 s39, s34
	s_mov_b32 s10, s39
	s_cbranch_scc0 .LBB0_110
	s_and_b64 vcc, exec, s[28:29]
	s_cbranch_vccz .LBB0_113
	s_barrier
